# v80 plus relaxed store-only waits in J layer-1 loop and F-phase loop with two per-channel vectors resident in registers
# speedup vs baseline: 1.0085x; 1.0085x over previous
.LBB0_1216:
	v_readlane_b32 s16, v254, 51
	s_lshl_b32 s70, s16, 11
	s_lshl_b64 s[18:19], s[70:71], 2
	v_readlane_b32 s17, v254, 52
	s_waitcnt lgkmcnt(0)
	s_add_u32 s16, s8, s18
	s_addc_u32 s17, s9, s19
	s_add_u32 s10, s10, s18
	v_writelane_b32 v254, s18, 58
	s_addc_u32 s11, s11, s19
	s_add_u32 s26, s14, 0x100000
	v_writelane_b32 v254, s19, 59
	v_lshlrev_b32_e32 v10, 2, v1
	v_readlane_b32 s8, v254, 45
	v_readlane_b32 s9, v254, 46
	s_addc_u32 s27, s15, 0
	s_and_b64 vcc, exec, s[8:9]
	v_ashrrev_i32_e32 v11, 31, v10
	s_mov_b32 s70, 0x21b1f000
	s_cbranch_vccnz .LBB0_1219
	s_add_u32 s8, s14, 0x1d91e000
	s_addc_u32 s9, s15, 0
	v_readlane_b32 s18, v253, 32
	v_readlane_b32 s19, v253, 33
	s_add_u32 s18, s8, s18
	v_lshlrev_b64 v[2:3], 1, v[10:11]
	s_addc_u32 s19, s9, s19
	v_lshl_add_u64 v[4:5], s[18:19], 0, v[2:3]
	global_load_dwordx2 v[6:7], v[4:5], off offset:3584
	global_load_dwordx2 v[8:9], v[4:5], off offset:3072
	global_load_dwordx2 v[26:27], v[4:5], off offset:2560
	global_load_dwordx2 v[32:33], v[4:5], off offset:2048
	global_load_dwordx2 v[34:35], v[4:5], off offset:1536
	global_load_dwordx2 v[38:39], v[4:5], off offset:1024
	global_load_dwordx2 v[42:43], v[4:5], off offset:512
	s_nop 0
	global_load_dwordx2 v[4:5], v[4:5], off
	v_lshl_add_u64 v[12:13], s[8:9], 0, v[2:3]
	v_readlane_b32 s8, v254, 57
	s_add_u32 s8, s26, s8
	s_addc_u32 s9, s27, 0
	s_add_u32 s22, s8, 0x6000
	s_addc_u32 s23, s9, 0
	v_readlane_b32 s18, v254, 12
	v_readlane_b32 s20, v254, 30
	s_add_u32 s24, s8, 0x8000
	v_readlane_b32 s19, v254, 13
	v_readlane_b32 s21, v254, 31
	s_addc_u32 s25, s9, 0
	v_readlane_b32 s8, v254, 20
	v_readlane_b32 s9, v254, 21
	s_waitcnt vmcnt(7)
	v_lshlrev_b32_e32 v16, 16, v6
	v_and_b32_e32 v17, 0xffff0000, v6
	v_lshlrev_b32_e32 v15, 16, v7
	v_and_b32_e32 v19, 0xffff0000, v7
	s_waitcnt vmcnt(6)
	v_lshlrev_b32_e32 v20, 16, v8
	v_and_b32_e32 v21, 0xffff0000, v8
	v_lshlrev_b32_e32 v22, 16, v9
	v_and_b32_e32 v23, 0xffff0000, v9
	s_waitcnt vmcnt(5)
	v_lshlrev_b32_e32 v24, 16, v26
	v_and_b32_e32 v62, 0xffff0000, v26
	v_lshlrev_b32_e32 v63, 16, v27
	v_and_b32_e32 v25, 0xffff0000, v27
	s_waitcnt vmcnt(4)
	v_lshlrev_b32_e32 v27, 16, v32
	v_and_b32_e32 v31, 0xffff0000, v32
	v_lshlrev_b32_e32 v29, 16, v33
	v_and_b32_e32 v33, 0xffff0000, v33
	s_waitcnt vmcnt(3)
	v_lshlrev_b32_e32 v36, 16, v34
	v_and_b32_e32 v37, 0xffff0000, v34
	v_lshlrev_b32_e32 v40, 16, v35
	v_and_b32_e32 v41, 0xffff0000, v35
	s_waitcnt vmcnt(2)
	v_lshlrev_b32_e32 v56, 16, v38
	v_and_b32_e32 v64, 0xffff0000, v38
	v_lshlrev_b32_e32 v65, 16, v39
	v_and_b32_e32 v57, 0xffff0000, v39
	s_waitcnt vmcnt(1)
	v_lshlrev_b32_e32 v59, 16, v42
	v_and_b32_e32 v69, 0xffff0000, v42
	v_lshlrev_b32_e32 v61, 16, v43
	v_and_b32_e32 v67, 0xffff0000, v43
	s_waitcnt vmcnt(0)
	v_lshlrev_b32_e32 v58, 16, v4
	v_and_b32_e32 v68, 0xffff0000, v4
	v_lshlrev_b32_e32 v60, 16, v5
	v_and_b32_e32 v66, 0xffff0000, v5
	v_lshlrev_b32_e32 v144, 4, v232
	v_add_u32_e32 v145, 0x1000, v144
	global_load_dwordx4 v[180:183], v144, s[16:17]
	global_load_dwordx4 v[212:215], v144, s[10:11]
	global_load_dwordx4 v[184:187], v144, s[16:17] offset:1024
	global_load_dwordx4 v[216:219], v144, s[10:11] offset:1024
	global_load_dwordx4 v[188:191], v144, s[16:17] offset:2048
	global_load_dwordx4 v[220:223], v144, s[10:11] offset:2048
	global_load_dwordx4 v[192:195], v144, s[16:17] offset:3072
	global_load_dwordx4 v[236:239], v144, s[10:11] offset:3072
	global_load_dwordx4 v[196:199], v145, s[16:17]
	global_load_dwordx4 v[240:243], v145, s[10:11]
	global_load_dwordx4 v[200:203], v145, s[16:17] offset:1024
	global_load_dwordx4 v[128:131], v145, s[10:11] offset:1024
	global_load_dwordx4 v[204:207], v145, s[16:17] offset:2048
	global_load_dwordx4 v[132:135], v145, s[10:11] offset:2048
	global_load_dwordx4 v[208:211], v145, s[16:17] offset:3072
	global_load_dwordx4 v[140:143], v145, s[10:11] offset:3072
	s_waitcnt vmcnt(0)
.LBB0_1218:
	v_pk_add_f32 v[2:3], v[58:59], v[68:69]
	v_pk_add_f32 v[4:5], v[60:61], v[66:67]
	v_pk_add_f32 v[6:7], v[64:65], v[56:57]
	v_pk_add_f32 v[2:3], v[2:3], v[4:5]
	v_add_f32_e32 v14, v20, v21
	v_add_f32_e32 v18, v22, v23
	v_and_b32_e32 v26, 64, v249
	v_pk_add_f32 v[4:5], v[6:7], v[6:7] op_sel:[0,1] op_sel_hi:[1,0]
	v_add_f32_e32 v2, 0, v2
	v_add_f32_e32 v28, v36, v37
	v_add_f32_e32 v32, v40, v41
	v_pk_add_f32 v[34:35], v[14:15], v[18:19]
	v_add_u32_e32 v14, 64, v26
	v_mov_b32_e32 v5, v31
	v_add_f32_e32 v26, v2, v3
	v_pk_add_f32 v[6:7], v[28:29], v[32:33]
	v_pk_add_f32 v[2:3], v[26:27], v[4:5]
	v_pk_add_f32 v[8:9], v[62:63], v[24:25]
	v_pk_add_f32 v[2:3], v[2:3], v[6:7]
	v_pk_add_f32 v[8:9], v[8:9], v[8:9] op_sel:[0,1] op_sel_hi:[1,0]
	v_pk_add_f32 v[2:3], v[2:3], v[2:3] op_sel:[0,1] op_sel_hi:[1,0]
	v_xor_b32_e32 v30, 1, v249
	v_mov_b32_e32 v9, v17
	v_mov_b32_e32 v3, v16
	v_cmp_lt_i32_e32 vcc, v30, v14
	v_pk_add_f32 v[2:3], v[2:3], v[8:9]
	v_xor_b32_e32 v38, 2, v249
	v_cndmask_b32_e32 v18, v249, v30, vcc
	v_pk_add_f32 v[2:3], v[2:3], v[34:35]
	v_lshlrev_b32_e32 v82, 2, v18
	v_add_f32_e32 v26, v2, v3
	ds_bpermute_b32 v84, v82, v26
	v_cmp_lt_i32_e32 vcc, v38, v14
	v_xor_b32_e32 v39, 4, v249
	v_xor_b32_e32 v42, 8, v249
	v_cndmask_b32_e32 v28, v249, v38, vcc
	v_lshlrev_b32_e32 v32, 2, v28
	s_waitcnt lgkmcnt(0)
	v_add_f32_e32 v26, v26, v84
	ds_bpermute_b32 v84, v32, v26
	v_cmp_lt_i32_e32 vcc, v39, v14
	v_xor_b32_e32 v43, 16, v249
	s_add_i32 s28, s8, s60
	v_cndmask_b32_e32 v30, v249, v39, vcc
	v_lshlrev_b32_e32 v30, 2, v30
	s_waitcnt lgkmcnt(0)
	v_add_f32_e32 v26, v26, v84
	ds_bpermute_b32 v84, v30, v26
	v_cmp_lt_i32_e32 vcc, v42, v14
	s_cmpk_lt_i32 s28, 0x2000
	v_xor_b32_e32 v44, 32, v249
	v_cndmask_b32_e32 v38, v249, v42, vcc
	v_lshlrev_b32_e32 v28, 2, v38
	s_waitcnt lgkmcnt(0)
	v_add_f32_e32 v26, v26, v84
	ds_bpermute_b32 v84, v28, v26
	v_cmp_lt_i32_e32 vcc, v43, v14
	s_cselect_b32 s8, s28, s8
	s_ashr_i32 s9, s8, 31
	v_cndmask_b32_e32 v39, v249, v43, vcc
	v_lshlrev_b32_e32 v18, 2, v39
	s_waitcnt lgkmcnt(0)
	v_add_f32_e32 v26, v26, v84
	ds_bpermute_b32 v84, v18, v26
	v_cmp_lt_i32_e32 vcc, v44, v14
	s_lshl_b64 s[8:9], s[8:9], 12
	s_add_u32 s30, s14, s20
	v_cndmask_b32_e32 v14, v249, v44, vcc
	v_lshlrev_b32_e32 v14, 2, v14
	s_waitcnt lgkmcnt(0)
	v_add_f32_e32 v26, v26, v84
	v_mov_b32_e32 v70, v1
	v_lshl_add_u64 v[4:5], v[12:13], 0, s[8:9]
	s_addc_u32 s31, s15, s21
	ds_bpermute_b32 v84, v14, v26
	global_load_dwordx2 v[54:55], v[4:5], off
	global_load_dwordx2 v[52:53], v[4:5], off offset:512
	global_load_dwordx2 v[50:51], v[4:5], off offset:1024
	global_load_dwordx2 v[48:49], v[4:5], off offset:1536
	global_load_dwordx2 v[46:47], v[4:5], off offset:2048
	global_load_dwordx2 v[44:45], v[4:5], off offset:2560
	global_load_dwordx2 v[42:43], v[4:5], off offset:3072
	global_load_dwordx2 v[38:39], v[4:5], off offset:3584
	s_add_u32 s8, s14, s18
	v_lshlrev_b32_e32 v4, 2, v70
	s_addc_u32 s9, s15, s19
	v_ashrrev_i32_e32 v5, 31, v4
	v_lshlrev_b64 v[6:7], 2, v[4:5]
	v_lshl_add_u64 v[4:5], v[4:5], 1, s[8:9]
	v_lshl_add_u64 v[76:77], s[16:17], 0, v[6:7]
	v_add_co_u32_e32 v34, vcc, s61, v4
	v_lshl_add_u64 v[74:75], s[10:11], 0, v[6:7]
	v_lshl_add_u64 v[78:79], s[30:31], 0, v[6:7]
	v_lshl_add_u64 v[72:73], s[24:25], 0, v[6:7]
	v_lshl_add_u64 v[70:71], s[22:23], 0, v[6:7]
	v_addc_co_u32_e32 v35, vcc, 0, v5, vcc
	s_nop 1
	v_mov_b64_e32 v[2:3], v[180:181]
	v_mov_b64_e32 v[4:5], v[182:183]
	s_nop 1
	v_mov_b64_e32 v[6:7], v[212:213]
	v_mov_b64_e32 v[8:9], v[214:215]
	s_waitcnt lgkmcnt(0)
	v_add_f32_e32 v26, v26, v84
	v_fmac_f32_e32 v66, 0xba000000, v26
	v_fmac_f32_e32 v68, 0xba000000, v26
	v_fmac_f32_e32 v67, 0xba000000, v26
	v_fmac_f32_e32 v69, 0xba000000, v26
	v_fmac_f32_e32 v64, 0xba000000, v26
	v_fmac_f32_e32 v57, 0xba000000, v26
	v_fmac_f32_e32 v65, 0xba000000, v26
	v_fmac_f32_e32 v60, 0xba000000, v26
	v_fmac_f32_e32 v58, 0xba000000, v26
	v_fmac_f32_e32 v61, 0xba000000, v26
	v_fmac_f32_e32 v59, 0xba000000, v26
	v_fmac_f32_e32 v56, 0xba000000, v26
	v_mov_b32_e32 v85, v69
	v_mov_b32_e32 v87, v68
	v_pk_mul_f32 v[68:69], v[68:69], v[68:69]
	v_mov_b32_e32 v89, v67
	v_mov_b32_e32 v91, v66
	v_pk_mul_f32 v[66:67], v[66:67], v[66:67]
	v_mov_b32_e32 v92, v65
	v_mov_b32_e32 v93, v57
	v_mov_b32_e32 v57, v64
	v_mov_b32_e32 v84, v59
	v_mov_b32_e32 v86, v58
	v_mov_b32_e32 v88, v61
	v_mov_b32_e32 v90, v60
	v_pk_fma_f32 v[58:59], v[58:59], v[58:59], v[68:69]
	v_pk_fma_f32 v[60:61], v[60:61], v[60:61], v[66:67]
	v_pk_mul_f32 v[66:67], v[92:93], v[92:93]
	v_pk_mul_f32 v[68:69], v[56:57], v[56:57]
	v_fmac_f32_e32 v36, 0xba000000, v26
	v_fmac_f32_e32 v40, 0xba000000, v26
	v_pk_add_f32 v[58:59], v[58:59], v[60:61]
	v_pk_mov_b32 v[60:61], v[68:69], v[66:67] op_sel:[1,0]
	v_mov_b32_e32 v69, v67
	v_fmac_f32_e32 v37, 0xba000000, v26
	v_fmac_f32_e32 v41, 0xba000000, v26
	v_fmac_f32_e32 v33, 0xba000000, v26
	v_fmac_f32_e32 v29, 0xba000000, v26
	v_fmac_f32_e32 v31, 0xba000000, v26
	v_fmac_f32_e32 v27, 0xba000000, v26
	v_fmac_f32_e32 v62, 0xba000000, v26
	v_fmac_f32_e32 v24, 0xba000000, v26
	v_fmac_f32_e32 v25, 0xba000000, v26
	v_fmac_f32_e32 v63, 0xba000000, v26
	v_fmac_f32_e32 v21, 0xba000000, v26
	v_fmac_f32_e32 v20, 0xba000000, v26
	v_fmac_f32_e32 v23, 0xba000000, v26
	v_fmac_f32_e32 v22, 0xba000000, v26
	v_fmac_f32_e32 v19, 0xba000000, v26
	v_fmac_f32_e32 v15, 0xba000000, v26
	v_fmac_f32_e32 v17, 0xba000000, v26
	v_fmac_f32_e32 v16, 0xba000000, v26
	v_mul_f32_e32 v26, v36, v36
	v_mul_f32_e32 v94, v40, v40
	v_pk_add_f32 v[60:61], v[60:61], v[68:69]
	v_mov_b32_e32 v64, v63
	v_mov_b32_e32 v65, v25
	v_mov_b32_e32 v25, v62
	v_pk_fma_f32 v[98:99], v[36:37], v[36:37], v[26:27] op_sel_hi:[1,1,0]
	v_pk_fma_f32 v[94:95], v[40:41], v[40:41], v[94:95] op_sel_hi:[1,1,0]
	v_pk_add_f32 v[58:59], v[58:59], v[58:59] op_sel_hi:[0,1]
	v_pk_add_f32 v[60:61], v[60:61], v[60:61] op_sel_hi:[0,1]
	v_pk_mul_f32 v[100:101], v[64:65], v[64:65]
	v_pk_mul_f32 v[102:103], v[24:25], v[24:25]
	v_mul_f32_e32 v98, v27, v27
	v_mul_f32_e32 v94, v31, v31
	v_mul_f32_e32 v58, v33, v33
	v_mul_f32_e32 v60, v29, v29
	v_pk_mov_b32 v[66:67], v[102:103], v[100:101] op_sel:[1,0]
	v_mov_b32_e32 v103, v101
	v_pk_add_f32 v[68:69], v[98:99], v[94:95]
	v_pk_add_f32 v[58:59], v[60:61], v[58:59]
	v_mul_f32_e32 v62, v20, v20
	v_mul_f32_e32 v96, v22, v22
	v_pk_add_f32 v[66:67], v[66:67], v[102:103]
	v_pk_add_f32 v[58:59], v[68:69], v[58:59]
	v_pk_fma_f32 v[62:63], v[20:21], v[20:21], v[62:63] op_sel_hi:[1,1,0]
	v_pk_fma_f32 v[96:97], v[22:23], v[22:23], v[96:97] op_sel_hi:[1,1,0]
	v_pk_add_f32 v[66:67], v[66:67], v[66:67] op_sel_hi:[0,1]
	v_pk_add_f32 v[58:59], v[58:59], v[58:59] op_sel_hi:[0,1]
	v_mul_f32_e32 v62, v16, v16
	v_mul_f32_e32 v96, v17, v17
	v_mul_f32_e32 v66, v15, v15
	v_mul_f32_e32 v58, v19, v19
	v_pk_add_f32 v[62:63], v[62:63], v[96:97]
	v_pk_add_f32 v[58:59], v[66:67], v[58:59]
	s_mov_b32 s8, 0x21b1e000
	v_pk_add_f32 v[58:59], v[62:63], v[58:59]
	v_add_co_u32_e32 v80, vcc, s8, v78
	v_add_f32_e32 v26, v58, v59
	ds_bpermute_b32 v58, v82, v26
	v_addc_co_u32_e32 v81, vcc, 0, v79, vcc
	v_add_co_u32_e32 v78, vcc, s70, v78
	s_waitcnt lgkmcnt(0)
	v_add_f32_e32 v26, v26, v58
	ds_bpermute_b32 v32, v32, v26
	v_addc_co_u32_e32 v79, vcc, 0, v79, vcc
	s_add_u32 s20, s20, s36
	s_addc_u32 s21, s21, s37
	s_waitcnt lgkmcnt(0)
	v_add_f32_e32 v26, v26, v32
	ds_bpermute_b32 v30, v30, v26
	s_add_u32 s18, s18, s38
	s_addc_u32 s19, s19, s39
	s_cmpk_gt_i32 s28, 0x1fff
	s_waitcnt vmcnt(7)
	v_and_b32_e32 v68, 0xffff0000, v54
	s_waitcnt lgkmcnt(0)
	v_add_f32_e32 v26, v26, v30
	ds_bpermute_b32 v28, v28, v26
	s_waitcnt vmcnt(6)
	v_and_b32_e32 v69, 0xffff0000, v52
	s_waitcnt lgkmcnt(0)
	v_add_f32_e32 v26, v26, v28
	ds_bpermute_b32 v18, v18, v26
	s_waitcnt lgkmcnt(0)
	v_add_f32_e32 v18, v26, v18
	ds_bpermute_b32 v14, v14, v18
	s_waitcnt lgkmcnt(0)
	v_add_f32_e32 v14, v18, v14
	v_fmamk_f32 v14, v14, 0x3a000000, v250
	v_mul_f32_e32 v18, 0x4f800000, v14
	v_cmp_gt_f32_e32 vcc, s96, v14
	s_nop 1
	v_cndmask_b32_e32 v14, v14, v18, vcc
	v_sqrt_f32_e32 v18, v14
	s_nop 0
	v_add_u32_e32 v26, -1, v18
	v_add_u32_e32 v28, 1, v18
	v_fma_f32 v30, -v26, v18, v14
	v_fma_f32 v32, -v28, v18, v14
	v_cmp_ge_f32_e64 s[8:9], 0, v30
	s_nop 1
	v_cndmask_b32_e64 v18, v18, v26, s[8:9]
	v_cmp_lt_f32_e64 s[8:9], 0, v32
	s_nop 1
	v_cndmask_b32_e64 v18, v18, v28, s[8:9]
	v_mul_f32_e32 v26, 0x37800000, v18
	v_cndmask_b32_e32 v18, v18, v26, vcc
	v_cmp_class_f32_e32 vcc, v14, v251
	s_nop 1
	v_cndmask_b32_e32 v14, v18, v14, vcc
	v_div_scale_f32 v18, s[8:9], v14, v14, 1.0
	v_rcp_f32_e32 v28, v18
	v_div_scale_f32 v26, vcc, 1.0, v14, 1.0
	s_mov_b32 s8, s28
	v_fma_f32 v30, -v18, v28, 1.0
	v_fmac_f32_e32 v28, v30, v28
	v_mul_f32_e32 v30, v26, v28
	v_fma_f32 v32, -v18, v30, v26
	v_fmac_f32_e32 v30, v32, v28
	v_fma_f32 v18, -v18, v30, v26
	v_div_fmas_f32 v18, v18, v28, v30
	v_div_fixup_f32 v14, v18, v14, 1.0
	v_pk_mul_f32 v[58:59], v[86:87], v[14:15] op_sel_hi:[1,0]
	v_pk_mul_f32 v[60:61], v[90:91], v[14:15] op_sel_hi:[1,0]
	s_waitcnt vmcnt(0)
	v_pk_fma_f32 v[2:3], v[2:3], v[58:59], v[6:7]
	v_pk_fma_f32 v[4:5], v[4:5], v[60:61], v[8:9]
	global_store_dwordx4 v[78:79], v[2:5], off offset:-4096
	global_load_dwordx4 v[6:9], v[72:73], off
	global_load_dwordx4 v[58:61], v[70:71], off
	v_pk_mul_f32 v[62:63], v[88:89], v[14:15] op_sel_hi:[1,0]
	v_pk_mul_f32 v[66:67], v[84:85], v[14:15] op_sel_hi:[1,0]
	v_pk_mul_f32 v[56:57], v[56:57], v[14:15] op_sel_hi:[1,0]
	v_pk_mul_f32 v[40:41], v[40:41], v[14:15] op_sel_hi:[1,0]
	v_pk_mul_f32 v[36:37], v[36:37], v[14:15] op_sel_hi:[1,0]
	v_mov_b32_e32 v32, v29
	v_mov_b32_e32 v30, v27
	v_pk_mul_f32 v[26:27], v[32:33], v[14:15] op_sel_hi:[1,0]
	v_pk_mul_f32 v[28:29], v[30:31], v[14:15] op_sel_hi:[1,0]
	v_pk_mul_f32 v[24:25], v[24:25], v[14:15] op_sel_hi:[1,0]
	v_pk_mul_f32 v[22:23], v[22:23], v[14:15] op_sel_hi:[1,0]
	v_pk_mul_f32 v[20:21], v[20:21], v[14:15] op_sel_hi:[1,0]
	v_mov_b32_e32 v18, v15
	v_pk_mul_f32 v[18:19], v[18:19], v[14:15] op_sel_hi:[1,0]
	v_lshlrev_b32_e32 v30, 16, v49
	v_and_b32_e32 v32, 0xffff0000, v46
	v_and_b32_e32 v33, 0xffff0000, v47
	v_mov_b32_e32 v31, v32
	s_waitcnt vmcnt(1)
	v_pk_add_f32 v[8:9], v[8:9], 1.0 op_sel_hi:[1,0]
	v_pk_add_f32 v[6:7], v[6:7], 1.0 op_sel_hi:[1,0]
	s_waitcnt vmcnt(0)
	v_pk_fma_f32 v[4:5], v[8:9], v[4:5], v[60:61]
	v_pk_fma_f32 v[2:3], v[6:7], v[2:3], v[58:59]
	v_cvt_pk_bf16_f32 v2, v2, v3
	v_cvt_pk_bf16_f32 v3, v4, v5
	global_store_dwordx2 v[34:35], v[2:3], off
	s_nop 1
	v_mov_b64_e32 v[2:3], v[184:185]
	v_mov_b64_e32 v[4:5], v[186:187]
	s_nop 0
	s_nop 1
	v_mov_b64_e32 v[6:7], v[216:217]
	v_mov_b64_e32 v[8:9], v[218:219]
	s_waitcnt vmcnt(0)
	v_pk_fma_f32 v[2:3], v[2:3], v[66:67], v[6:7]
	v_pk_fma_f32 v[4:5], v[4:5], v[62:63], v[8:9]
	global_store_dwordx4 v[80:81], v[2:5], off offset:1024
	global_load_dwordx4 v[6:9], v[72:73], off offset:1024
	global_load_dwordx4 v[58:61], v[70:71], off offset:1024
	v_and_b32_e32 v62, 0xffff0000, v44
	v_lshlrev_b32_e32 v63, 16, v45
	v_and_b32_e32 v66, 0xffff0000, v55
	v_and_b32_e32 v67, 0xffff0000, v53
	s_waitcnt vmcnt(1)
	v_pk_add_f32 v[8:9], v[8:9], 1.0 op_sel_hi:[1,0]
	v_pk_add_f32 v[6:7], v[6:7], 1.0 op_sel_hi:[1,0]
	s_waitcnt vmcnt(0)
	v_pk_fma_f32 v[4:5], v[8:9], v[4:5], v[60:61]
	v_pk_fma_f32 v[2:3], v[6:7], v[2:3], v[58:59]
	v_cvt_pk_bf16_f32 v2, v2, v3
	v_cvt_pk_bf16_f32 v3, v4, v5
	global_store_dwordx2 v[34:35], v[2:3], off offset:512
	s_nop 1
	v_mov_b64_e32 v[2:3], v[188:189]
	v_mov_b64_e32 v[4:5], v[190:191]
	s_nop 0
	s_nop 1
	v_mov_b64_e32 v[6:7], v[220:221]
	v_mov_b64_e32 v[8:9], v[222:223]
	v_pk_mul_f32 v[58:59], v[92:93], v[14:15] op_sel_hi:[1,0]
	v_lshlrev_b32_e32 v60, 16, v55
	v_lshlrev_b32_e32 v61, 16, v53
	s_waitcnt vmcnt(0)
	v_pk_fma_f32 v[2:3], v[2:3], v[56:57], v[6:7]
	v_pk_fma_f32 v[4:5], v[4:5], v[58:59], v[8:9]
	global_store_dwordx4 v[80:81], v[2:5], off offset:2048
	global_load_dwordx4 v[6:9], v[72:73], off offset:2048
	global_load_dwordx4 v[56:59], v[70:71], off offset:2048
	s_waitcnt vmcnt(1)
	v_pk_add_f32 v[8:9], v[8:9], 1.0 op_sel_hi:[1,0]
	v_pk_add_f32 v[6:7], v[6:7], 1.0 op_sel_hi:[1,0]
	s_waitcnt vmcnt(0)
	v_pk_fma_f32 v[4:5], v[4:5], v[8:9], v[58:59]
	v_pk_fma_f32 v[2:3], v[2:3], v[6:7], v[56:57]
	v_cvt_pk_bf16_f32 v2, v2, v3
	v_cvt_pk_bf16_f32 v3, v4, v5
	global_store_dwordx2 v[34:35], v[2:3], off offset:1024
	s_nop 1
	v_mov_b64_e32 v[2:3], v[192:193]
	v_mov_b64_e32 v[4:5], v[194:195]
	s_nop 0
	s_nop 1
	v_mov_b64_e32 v[6:7], v[236:237]
	v_mov_b64_e32 v[8:9], v[238:239]
	s_waitcnt vmcnt(0)
	v_pk_fma_f32 v[2:3], v[36:37], v[2:3], v[6:7]
	v_pk_fma_f32 v[4:5], v[40:41], v[4:5], v[8:9]
	global_store_dwordx4 v[80:81], v[2:5], off offset:3072
	global_load_dwordx4 v[6:9], v[72:73], off offset:3072
	global_load_dwordx4 v[56:59], v[70:71], off offset:3072
	v_add_co_u32_e32 v36, vcc, s82, v76
	s_waitcnt vmcnt(1)
	v_pk_add_f32 v[8:9], v[8:9], 1.0 op_sel_hi:[1,0]
	v_pk_add_f32 v[6:7], v[6:7], 1.0 op_sel_hi:[1,0]
	s_waitcnt vmcnt(0)
	v_pk_fma_f32 v[4:5], v[4:5], v[8:9], v[58:59]
	v_pk_fma_f32 v[2:3], v[2:3], v[6:7], v[56:57]
	s_nop 0
	s_nop 0
	s_nop 0
	s_nop 0
	s_nop 0
	s_nop 0
	s_nop 0
	s_nop 0
	s_nop 0
	s_nop 0
	v_addc_co_u32_e32 v37, vcc, 0, v77, vcc
	v_cvt_pk_bf16_f32 v2, v2, v3
	v_cvt_pk_bf16_f32 v3, v4, v5
	v_add_co_u32_e32 v40, vcc, s82, v74
	global_store_dwordx2 v[34:35], v[2:3], off offset:1536
	s_nop 0
	v_addc_co_u32_e32 v41, vcc, 0, v75, vcc
	s_nop 1
	v_mov_b64_e32 v[2:3], v[196:197]
	v_mov_b64_e32 v[4:5], v[198:199]
	s_nop 1
	v_mov_b64_e32 v[6:7], v[240:241]
	v_mov_b64_e32 v[8:9], v[242:243]
	v_add_co_u32_e32 v56, vcc, s82, v72
	s_waitcnt vmcnt(0)
	v_pk_fma_f32 v[2:3], v[28:29], v[2:3], v[6:7]
	v_addc_co_u32_e32 v57, vcc, 0, v73, vcc
	v_pk_fma_f32 v[4:5], v[26:27], v[4:5], v[8:9]
	v_add_co_u32_e32 v58, vcc, s82, v70
	global_store_dwordx4 v[78:79], v[2:5], off
	s_nop 0
	v_addc_co_u32_e32 v59, vcc, 0, v71, vcc
	global_load_dwordx4 v[6:9], v[56:57], off
	global_load_dwordx4 v[26:29], v[58:59], off
	s_waitcnt vmcnt(1)
	v_pk_add_f32 v[8:9], v[8:9], 1.0 op_sel_hi:[1,0]
	v_pk_add_f32 v[6:7], v[6:7], 1.0 op_sel_hi:[1,0]
	s_waitcnt vmcnt(0)
	v_pk_fma_f32 v[4:5], v[4:5], v[8:9], v[28:29]
	v_pk_fma_f32 v[2:3], v[2:3], v[6:7], v[26:27]
	v_cvt_pk_bf16_f32 v2, v2, v3
	v_cvt_pk_bf16_f32 v3, v4, v5
	global_store_dwordx2 v[34:35], v[2:3], off offset:2048
	s_nop 1
	v_mov_b64_e32 v[2:3], v[200:201]
	v_mov_b64_e32 v[4:5], v[202:203]
	s_nop 0
	s_nop 1
	v_mov_b64_e32 v[6:7], v[128:129]
	v_mov_b64_e32 v[8:9], v[130:131]
	v_pk_mul_f32 v[26:27], v[64:65], v[14:15] op_sel_hi:[1,0]
	v_pk_mul_f32 v[14:15], v[16:17], v[14:15] op_sel_hi:[1,0]
	v_and_b32_e32 v28, 0xffff0000, v48
	v_lshlrev_b32_e32 v29, 16, v47
	v_lshlrev_b32_e32 v47, 16, v43
	v_and_b32_e32 v43, 0xffff0000, v43
	v_and_b32_e32 v64, 0xffff0000, v50
	v_lshlrev_b32_e32 v65, 16, v51
	s_waitcnt vmcnt(0)
	v_pk_fma_f32 v[2:3], v[24:25], v[2:3], v[6:7]
	v_pk_fma_f32 v[4:5], v[26:27], v[4:5], v[8:9]
	global_store_dwordx4 v[78:79], v[2:5], off offset:1024
	global_load_dwordx4 v[6:9], v[56:57], off offset:1024
	global_load_dwordx4 v[24:27], v[58:59], off offset:1024
	s_waitcnt vmcnt(1)
	v_pk_add_f32 v[8:9], v[8:9], 1.0 op_sel_hi:[1,0]
	v_pk_add_f32 v[6:7], v[6:7], 1.0 op_sel_hi:[1,0]
	s_waitcnt vmcnt(0)
	v_pk_fma_f32 v[4:5], v[4:5], v[8:9], v[26:27]
	v_pk_fma_f32 v[2:3], v[2:3], v[6:7], v[24:25]
	v_cvt_pk_bf16_f32 v2, v2, v3
	v_cvt_pk_bf16_f32 v3, v4, v5
	global_store_dwordx2 v[34:35], v[2:3], off offset:2560
	s_nop 1
	v_mov_b64_e32 v[2:3], v[204:205]
	v_mov_b64_e32 v[4:5], v[206:207]
	s_nop 0
	s_nop 1
	v_mov_b64_e32 v[6:7], v[132:133]
	v_mov_b64_e32 v[8:9], v[134:135]
	v_lshlrev_b32_e32 v26, 16, v48
	v_lshlrev_b32_e32 v27, 16, v46
	v_lshlrev_b32_e32 v46, 16, v44
	v_and_b32_e32 v44, 0xffff0000, v45
	v_lshlrev_b32_e32 v45, 16, v42
	v_and_b32_e32 v42, 0xffff0000, v42
	v_lshlrev_b32_e32 v48, 16, v38
	v_and_b32_e32 v38, 0xffff0000, v38
	v_mov_b32_e32 v24, v46
	v_mov_b32_e32 v25, v44
	v_mov_b32_e32 v16, v48
	v_mov_b32_e32 v17, v38
	s_waitcnt vmcnt(0)
	v_pk_fma_f32 v[2:3], v[20:21], v[2:3], v[6:7]
	v_pk_fma_f32 v[4:5], v[22:23], v[4:5], v[8:9]
	global_store_dwordx4 v[78:79], v[2:5], off offset:2048
	global_load_dwordx4 v[6:9], v[56:57], off offset:2048
	global_load_dwordx4 v[20:23], v[58:59], off offset:2048
	s_waitcnt vmcnt(1)
	v_pk_add_f32 v[8:9], v[8:9], 1.0 op_sel_hi:[1,0]
	v_pk_add_f32 v[6:7], v[6:7], 1.0 op_sel_hi:[1,0]
	s_waitcnt vmcnt(0)
	v_pk_fma_f32 v[4:5], v[4:5], v[8:9], v[22:23]
	v_pk_fma_f32 v[2:3], v[2:3], v[6:7], v[20:21]
	v_cvt_pk_bf16_f32 v2, v2, v3
	v_cvt_pk_bf16_f32 v3, v4, v5
	global_store_dwordx2 v[34:35], v[2:3], off offset:3072
	s_nop 1
	v_mov_b64_e32 v[2:3], v[208:209]
	v_mov_b64_e32 v[4:5], v[210:211]
	s_nop 0
	s_nop 1
	v_mov_b64_e32 v[6:7], v[140:141]
	v_mov_b64_e32 v[8:9], v[142:143]
	v_lshlrev_b32_e32 v40, 16, v39
	v_and_b32_e32 v39, 0xffff0000, v39
	v_and_b32_e32 v41, 0xffff0000, v49
	v_mov_b32_e32 v36, v26
	v_mov_b32_e32 v37, v28
	v_mov_b32_e32 v20, v45
	v_mov_b32_e32 v21, v42
	v_mov_b32_e32 v22, v47
	v_mov_b32_e32 v23, v43
	s_waitcnt vmcnt(0)
	v_pk_fma_f32 v[2:3], v[14:15], v[2:3], v[6:7]
	v_pk_fma_f32 v[4:5], v[18:19], v[4:5], v[8:9]
	global_store_dwordx4 v[78:79], v[2:5], off offset:3072
	global_load_dwordx4 v[6:9], v[56:57], off offset:3072
	global_load_dwordx4 v[70:73], v[58:59], off offset:3072
	v_lshlrev_b32_e32 v58, 16, v54
	v_lshlrev_b32_e32 v59, 16, v52
	v_lshlrev_b32_e32 v56, 16, v50
	v_and_b32_e32 v57, 0xffff0000, v51
	v_mov_b32_e32 v15, v40
	v_mov_b32_e32 v40, v30
	v_mov_b32_e32 v19, v39
	s_waitcnt vmcnt(1)
	v_pk_add_f32 v[8:9], v[8:9], 1.0 op_sel_hi:[1,0]
	v_pk_add_f32 v[6:7], v[6:7], 1.0 op_sel_hi:[1,0]
	s_waitcnt vmcnt(0)
	v_pk_fma_f32 v[4:5], v[4:5], v[8:9], v[72:73]
	v_pk_fma_f32 v[2:3], v[2:3], v[6:7], v[70:71]
	v_bfe_u32 v8, v4, 16, 1
	v_bfe_u32 v6, v2, 16, 1
	v_bfe_u32 v7, v3, 16, 1
	v_bfe_u32 v9, v5, 16, 1
	v_add3_u32 v2, v2, v6, s73
	v_add3_u32 v4, v4, v8, s73
	v_add3_u32 v3, v3, v7, s73
	v_add3_u32 v5, v5, v9, s73
	v_lshrrev_b32_e32 v2, 16, v2
	v_lshrrev_b32_e32 v4, 16, v4
	v_and_or_b32 v2, v3, s33, v2
	v_and_or_b32 v3, v5, s33, v4
	global_store_dwordx2 v[34:35], v[2:3], off offset:3584
	s_cbranch_scc0 .LBB0_1218

.LBB0_1705:
	s_mov_b64 s[10:11], s[0:1]
	v_mov_b32_e32 v2, v0
	s_mov_b64 s[22:23], s[44:45]
	v_mov_b32_e32 v1, v232
	s_mov_b64 s[18:19], s[46:47]
	s_add_i32 s9, s60, s8
	v_lshlrev_b32_e32 v2, 2, v1
	v_ashrrev_i32_e32 v3, 31, v2
	v_lshlrev_b64 v[4:5], 1, v[2:3]
	v_lshl_add_u64 v[8:9], s[18:19], 0, v[4:5]
	v_lshl_add_u64 v[8:9], v[8:9], 0, s[16:17]
	global_load_dwordx2 v[56:57], v[8:9], off offset:-3584
	global_load_dwordx2 v[62:63], v[8:9], off offset:-3072
	global_load_dwordx2 v[66:67], v[8:9], off offset:-2560
	global_load_dwordx2 v[10:11], v[8:9], off offset:-2048
	s_cmpk_lt_i32 s9, 0x2000
	s_cselect_b32 s24, s9, s8
	s_ashr_i32 s25, s24, 31
	s_lshl_b64 s[20:21], s[24:25], 12
	s_add_u32 s18, s18, s20
	s_addc_u32 s19, s19, s21
	v_lshl_add_u64 v[4:5], s[18:19], 0, v[4:5]
	v_lshl_add_u64 v[224:225], v[4:5], 0, s[54:55]
	global_load_dwordx2 v[92:93], v[8:9], off offset:-1536
	global_load_dwordx2 v[98:99], v[8:9], off offset:-1024
	global_load_dwordx2 v[100:101], v[8:9], off offset:-512
	global_load_dwordx2 v[108:109], v[8:9], off
	global_load_dwordx2 v[110:111], v[224:225], off
	global_load_dwordx2 v[118:119], v[224:225], off offset:512
	global_load_dwordx2 v[120:121], v[224:225], off offset:1024
	global_load_dwordx2 v[122:123], v[224:225], off offset:1536
	global_load_dwordx2 v[144:145], v[224:225], off offset:2048
	global_load_dwordx2 v[146:147], v[224:225], off offset:2560
	global_load_dwordx2 v[152:153], v[224:225], off offset:3072
	global_load_dwordx2 v[154:155], v[224:225], off offset:3584
	v_and_b32_e32 v7, 64, v249
	v_add_u32_e32 v12, 64, v7
	v_xor_b32_e32 v7, 1, v249
	s_waitcnt vmcnt(3)
	v_lshlrev_b32_e32 v68, 16, v56
	s_waitcnt vmcnt(2)
	v_lshlrev_b32_e32 v69, 16, v62
	v_and_b32_e32 v71, 0xffff0000, v62
	s_waitcnt vmcnt(0)
	v_lshlrev_b32_e32 v58, 16, v10
	v_and_b32_e32 v59, 0xffff0000, v10
	v_lshlrev_b32_e32 v60, 16, v11
	v_and_b32_e32 v61, 0xffff0000, v11
	s_nop 1
	v_mov_b64_e32 v[10:11], v[92:93]
	v_and_b32_e32 v70, 0xffff0000, v56
	v_lshlrev_b32_e32 v65, 16, v63
	v_lshlrev_b32_e32 v64, 16, v57
	v_and_b32_e32 v75, 0xffff0000, v63
	v_and_b32_e32 v74, 0xffff0000, v57
	v_pk_add_f32 v[56:57], v[64:65], v[74:75]
	v_lshlrev_b32_e32 v63, 16, v67
	v_lshlrev_b32_e32 v62, 16, v66
	v_and_b32_e32 v73, 0xffff0000, v67
	v_and_b32_e32 v72, 0xffff0000, v66
	v_add_f32_e32 v54, v58, v59
	v_add_f32_e32 v52, v60, v61
	s_nop 0
	v_lshlrev_b32_e32 v51, 16, v10
	v_and_b32_e32 v49, 0xffff0000, v10
	v_lshlrev_b32_e32 v55, 16, v11
	v_and_b32_e32 v53, 0xffff0000, v11
	s_nop 1
	v_mov_b64_e32 v[76:77], v[98:99]
	s_nop 1
	v_mov_b64_e32 v[10:11], v[100:101]
	s_nop 0
	v_lshlrev_b32_e32 v46, 16, v11
	s_nop 1
	v_mov_b64_e32 v[8:9], v[108:109]
	v_and_b32_e32 v47, 0xffff0000, v11
	v_lshlrev_b32_e32 v40, 16, v10
	v_and_b32_e32 v41, 0xffff0000, v10
	v_add_f32_e32 v44, v40, v41
	v_add_f32_e32 v42, v46, v47
	s_nop 0
	v_lshlrev_b32_e32 v38, 16, v8
	v_and_b32_e32 v39, 0xffff0000, v8
	v_lshlrev_b32_e32 v45, 16, v9
	v_and_b32_e32 v43, 0xffff0000, v9
	v_lshl_add_u64 v[8:9], v[4:5], 0, s[54:55]
	v_add_co_u32_e32 v4, vcc, s27, v4
	s_nop 1
	v_addc_co_u32_e32 v5, vcc, 0, v5, vcc
	s_nop 1
	v_mov_b64_e32 v[34:35], v[110:111]
	s_nop 1
	v_mov_b64_e32 v[36:37], v[118:119]
	s_nop 1
	v_mov_b64_e32 v[32:33], v[120:121]
	s_nop 0
	s_nop 1
	v_mov_b64_e32 v[4:5], v[122:123]
	v_cmp_lt_i32_e32 vcc, v7, v12
	s_nop 0
	v_lshlrev_b32_e32 v26, 16, v4
	v_and_b32_e32 v27, 0xffff0000, v4
	v_lshlrev_b32_e32 v28, 16, v5
	v_and_b32_e32 v29, 0xffff0000, v5
	s_nop 1
	v_mov_b64_e32 v[4:5], v[144:145]
	v_cndmask_b32_e32 v7, v249, v7, vcc
	v_lshlrev_b32_e32 v7, 2, v7
	v_add_f32_e32 v24, v26, v27
	s_nop 0
	v_lshlrev_b32_e32 v21, 16, v4
	v_and_b32_e32 v19, 0xffff0000, v4
	v_lshlrev_b32_e32 v25, 16, v5
	v_and_b32_e32 v23, 0xffff0000, v5
	s_nop 1
	v_mov_b64_e32 v[30:31], v[146:147]
	s_nop 1
	v_mov_b64_e32 v[4:5], v[152:153]
	s_load_dwordx4 s[28:31], s[10:11], 0xb0
	s_waitcnt lgkmcnt(0)
	s_add_u32 s20, s28, 0x2000
	s_addc_u32 s21, s29, 0
	s_add_u32 s18, s30, 0x2000
	s_addc_u32 s19, s31, 0
	s_nop 0
	v_lshlrev_b32_e32 v14, 16, v4
	v_and_b32_e32 v15, 0xffff0000, v4
	v_lshlrev_b32_e32 v16, 16, v5
	v_and_b32_e32 v17, 0xffff0000, v5
	s_nop 1
	v_mov_b64_e32 v[4:5], v[154:155]
	s_nop 0
	v_lshlrev_b32_e32 v8, 16, v4
	v_and_b32_e32 v9, 0xffff0000, v4
	v_lshlrev_b32_e32 v13, 16, v5
	v_and_b32_e32 v11, 0xffff0000, v5
	v_pk_add_f32 v[4:5], v[68:69], v[70:71]
	s_nop 0
	v_pk_add_f32 v[4:5], v[4:5], v[56:57]
	v_pk_add_f32 v[56:57], v[54:55], v[52:53]
	v_add_f32_e32 v4, 0, v4
	v_add_f32_e32 v50, v4, v5
	v_pk_add_f32 v[4:5], v[62:63], v[72:73]
	s_nop 0
	v_pk_add_f32 v[4:5], v[4:5], v[4:5] op_sel:[0,1] op_sel_hi:[1,0]
	s_nop 0
	v_mov_b32_e32 v5, v49
	v_pk_add_f32 v[4:5], v[50:51], v[4:5]
	s_nop 0
	v_pk_add_f32 v[66:67], v[4:5], v[56:57]
	v_lshlrev_b32_e32 v57, 16, v77
	v_lshlrev_b32_e32 v56, 16, v76
	v_and_b32_e32 v5, 0xffff0000, v77
	v_and_b32_e32 v4, 0xffff0000, v76
	v_pk_add_f32 v[76:77], v[56:57], v[4:5]
	v_pk_add_f32 v[66:67], v[66:67], v[66:67] op_sel:[0,1] op_sel_hi:[1,0]
	v_pk_add_f32 v[76:77], v[76:77], v[76:77] op_sel:[0,1] op_sel_hi:[1,0]
	v_mov_b32_e32 v67, v38
	v_mov_b32_e32 v77, v39
	v_pk_add_f32 v[66:67], v[66:67], v[76:77]
	v_pk_add_f32 v[76:77], v[44:45], v[42:43]
	v_lshlrev_b32_e32 v44, 16, v35
	v_pk_add_f32 v[66:67], v[66:67], v[76:77]
	s_nop 0
	v_add_f32_e32 v10, v66, v67
	ds_bpermute_b32 v18, v7, v10
	s_waitcnt lgkmcnt(0)
	v_add_f32_e32 v10, v10, v18
	v_xor_b32_e32 v18, 2, v249
	v_cmp_lt_i32_e32 vcc, v18, v12
	s_nop 1
	v_cndmask_b32_e32 v18, v249, v18, vcc
	v_lshlrev_b32_e32 v18, 2, v18
	ds_bpermute_b32 v20, v18, v10
	s_waitcnt lgkmcnt(0)
	v_add_f32_e32 v10, v10, v20
	v_xor_b32_e32 v20, 4, v249
	v_cmp_lt_i32_e32 vcc, v20, v12
	s_nop 1
	v_cndmask_b32_e32 v20, v249, v20, vcc
	v_lshlrev_b32_e32 v50, 2, v20
	ds_bpermute_b32 v20, v50, v10
	s_waitcnt lgkmcnt(0)
	v_add_f32_e32 v10, v10, v20
	v_xor_b32_e32 v20, 8, v249
	v_cmp_lt_i32_e32 vcc, v20, v12
	s_nop 1
	v_cndmask_b32_e32 v20, v249, v20, vcc
	v_lshlrev_b32_e32 v54, 2, v20
	ds_bpermute_b32 v20, v54, v10
	s_waitcnt lgkmcnt(0)
	v_add_f32_e32 v10, v10, v20
	v_xor_b32_e32 v20, 16, v249
	v_cmp_lt_i32_e32 vcc, v20, v12
	s_nop 1
	v_cndmask_b32_e32 v20, v249, v20, vcc
	v_lshlrev_b32_e32 v82, 2, v20
	ds_bpermute_b32 v20, v82, v10
	s_waitcnt lgkmcnt(0)
	v_add_f32_e32 v10, v10, v20
	v_xor_b32_e32 v20, 32, v249
	v_cmp_lt_i32_e32 vcc, v20, v12
	s_nop 1
	v_cndmask_b32_e32 v12, v249, v20, vcc
	v_lshlrev_b32_e32 v84, 2, v12
	ds_bpermute_b32 v12, v84, v10
	s_waitcnt lgkmcnt(0)
	v_add_f32_e32 v12, v10, v12
	v_fmac_f32_e32 v70, 0xba000000, v12
	v_fmac_f32_e32 v71, 0xba000000, v12
	v_fmac_f32_e32 v74, 0xba000000, v12
	v_fmac_f32_e32 v68, 0xba000000, v12
	v_fmac_f32_e32 v75, 0xba000000, v12
	v_fmac_f32_e32 v69, 0xba000000, v12
	v_mov_b32_e32 v67, v71
	v_mov_b32_e32 v79, v70
	v_pk_mul_f32 v[70:71], v[70:71], v[70:71]
	v_fmac_f32_e32 v64, 0xba000000, v12
	v_fmac_f32_e32 v65, 0xba000000, v12
	v_mov_b32_e32 v66, v69
	v_mov_b32_e32 v78, v68
	v_pk_fma_f32 v[68:69], v[68:69], v[68:69], v[70:71]
	v_mov_b32_e32 v71, v75
	v_mov_b32_e32 v81, v74
	v_pk_mul_f32 v[74:75], v[74:75], v[74:75]
	v_mov_b32_e32 v70, v65
	v_mov_b32_e32 v80, v64
	v_pk_fma_f32 v[64:65], v[64:65], v[64:65], v[74:75]
	v_fmac_f32_e32 v72, 0xba000000, v12
	v_fmac_f32_e32 v73, 0xba000000, v12
	v_fmac_f32_e32 v63, 0xba000000, v12
	v_pk_add_f32 v[64:65], v[68:69], v[64:65]
	v_fmac_f32_e32 v62, 0xba000000, v12
	v_mov_b32_e32 v68, v63
	v_mov_b32_e32 v69, v73
	v_mov_b32_e32 v63, v72
	v_pk_mul_f32 v[74:75], v[68:69], v[68:69]
	v_pk_mul_f32 v[72:73], v[62:63], v[62:63]
	v_fmac_f32_e32 v58, 0xba000000, v12
	v_pk_mov_b32 v[76:77], v[72:73], v[74:75] op_sel:[1,0]
	v_mov_b32_e32 v73, v75
	v_fmac_f32_e32 v59, 0xba000000, v12
	v_fmac_f32_e32 v60, 0xba000000, v12
	v_mul_f32_e32 v10, v58, v58
	v_pk_add_f32 v[72:73], v[76:77], v[72:73]
	v_fmac_f32_e32 v61, 0xba000000, v12
	v_pk_fma_f32 v[74:75], v[58:59], v[58:59], v[10:11] op_sel_hi:[1,1,0]
	v_mul_f32_e32 v10, v60, v60
	v_pk_add_f32 v[64:65], v[64:65], v[64:65] op_sel_hi:[0,1]
	v_pk_add_f32 v[72:73], v[72:73], v[72:73] op_sel_hi:[0,1]
	v_pk_fma_f32 v[76:77], v[60:61], v[60:61], v[10:11] op_sel_hi:[1,1,0]
	v_fmac_f32_e32 v53, 0xba000000, v12
	v_fmac_f32_e32 v55, 0xba000000, v12
	v_fmac_f32_e32 v49, 0xba000000, v12
	v_fmac_f32_e32 v51, 0xba000000, v12
	v_mul_f32_e32 v74, v51, v51
	v_mul_f32_e32 v76, v49, v49
	v_mul_f32_e32 v72, v55, v55
	v_mul_f32_e32 v64, v53, v53
	v_pk_add_f32 v[74:75], v[74:75], v[76:77]
	v_pk_add_f32 v[64:65], v[72:73], v[64:65]
	v_fmac_f32_e32 v4, 0xba000000, v12
	v_pk_add_f32 v[64:65], v[74:75], v[64:65]
	v_fmac_f32_e32 v5, 0xba000000, v12
	v_fmac_f32_e32 v57, 0xba000000, v12
	v_pk_add_f32 v[72:73], v[64:65], v[64:65] op_sel_hi:[0,1]
	v_fmac_f32_e32 v56, 0xba000000, v12
	v_mov_b32_e32 v64, v57
	v_mov_b32_e32 v65, v5
	v_mov_b32_e32 v57, v4
	v_pk_mul_f32 v[74:75], v[64:65], v[64:65]
	v_pk_mul_f32 v[4:5], v[56:57], v[56:57]
	v_fmac_f32_e32 v40, 0xba000000, v12
	v_pk_mov_b32 v[76:77], v[4:5], v[74:75] op_sel:[1,0]
	v_mov_b32_e32 v5, v75
	v_pk_add_f32 v[4:5], v[76:77], v[4:5]
	v_fmac_f32_e32 v41, 0xba000000, v12
	v_pk_add_f32 v[4:5], v[4:5], v[4:5] op_sel_hi:[0,1]
	v_fmac_f32_e32 v46, 0xba000000, v12
	v_mul_f32_e32 v4, v40, v40
	v_fmac_f32_e32 v47, 0xba000000, v12
	v_pk_fma_f32 v[74:75], v[40:41], v[40:41], v[4:5] op_sel_hi:[1,1,0]
	v_mul_f32_e32 v4, v46, v46
	v_pk_fma_f32 v[76:77], v[46:47], v[46:47], v[4:5] op_sel_hi:[1,1,0]
	v_fmac_f32_e32 v43, 0xba000000, v12
	v_fmac_f32_e32 v45, 0xba000000, v12
	v_fmac_f32_e32 v39, 0xba000000, v12
	v_fmac_f32_e32 v38, 0xba000000, v12
	v_mul_f32_e32 v74, v38, v38
	v_mul_f32_e32 v76, v39, v39
	v_mul_f32_e32 v4, v45, v45
	v_mul_f32_e32 v72, v43, v43
	v_pk_add_f32 v[74:75], v[74:75], v[76:77]
	v_pk_add_f32 v[4:5], v[4:5], v[72:73]
	v_lshlrev_b64 v[72:73], 2, v[2:3]
	v_pk_add_f32 v[4:5], v[74:75], v[4:5]
	v_lshl_add_u64 v[76:77], s[20:21], 0, v[72:73]
	v_add_f32_e32 v4, v4, v5
	ds_bpermute_b32 v5, v7, v4
	v_lshl_add_u64 v[74:75], s[18:19], 0, v[72:73]
	s_nop 1
	v_mov_b64_e32 v[86:87], v[212:213]
	v_mov_b64_e32 v[88:89], v[214:215]
	v_lshl_add_u64 v[72:73], s[22:23], 0, v[72:73]
	v_lshl_add_u64 v[72:73], v[72:73], 0, s[14:15]
	s_waitcnt lgkmcnt(0)
	v_add_f32_e32 v4, v4, v5
	ds_bpermute_b32 v5, v18, v4
	v_mov_b32_e32 v52, v55
	v_mov_b32_e32 v48, v51
	v_mov_b32_e32 v42, v45
	v_lshlrev_b32_e32 v45, 16, v37
	s_waitcnt lgkmcnt(0)
	v_add_f32_e32 v4, v4, v5
	ds_bpermute_b32 v5, v50, v4
	s_waitcnt lgkmcnt(0)
	v_add_f32_e32 v4, v4, v5
	ds_bpermute_b32 v5, v54, v4
	s_waitcnt lgkmcnt(0)
	v_add_f32_e32 v4, v4, v5
	ds_bpermute_b32 v5, v82, v4
	s_waitcnt lgkmcnt(0)
	v_add_f32_e32 v4, v4, v5
	ds_bpermute_b32 v5, v84, v4
	s_waitcnt lgkmcnt(0)
	v_add_f32_e32 v4, v4, v5
	v_fmamk_f32 v4, v4, 0x3a000000, v250
	v_cmp_gt_f32_e32 vcc, s96, v4
	v_mul_f32_e32 v5, 0x4f800000, v4
	s_nop 0
	v_cndmask_b32_e32 v4, v4, v5, vcc
	v_sqrt_f32_e32 v5, v4
	s_nop 0
	v_add_u32_e32 v10, -1, v5
	v_fma_f32 v12, -v10, v5, v4
	v_cmp_ge_f32_e64 s[10:11], 0, v12
	v_add_u32_e32 v12, 1, v5
	s_nop 0
	v_cndmask_b32_e64 v10, v5, v10, s[10:11]
	v_fma_f32 v5, -v12, v5, v4
	v_cmp_lt_f32_e64 s[10:11], 0, v5
	s_nop 1
	v_cndmask_b32_e64 v5, v10, v12, s[10:11]
	v_mul_f32_e32 v10, 0x37800000, v5
	v_cndmask_b32_e32 v5, v5, v10, vcc
	v_cmp_class_f32_e32 vcc, v4, v251
	s_nop 1
	v_cndmask_b32_e32 v4, v5, v4, vcc
	v_div_scale_f32 v5, s[10:11], v4, v4, 1.0
	v_rcp_f32_e32 v10, v5
	s_lshl_b64 s[10:11], s[24:25], 13
	s_add_u32 s22, s22, s10
	s_addc_u32 s23, s23, s11
	v_fma_f32 v12, -v5, v10, 1.0
	v_fmac_f32_e32 v10, v12, v10
	v_div_scale_f32 v12, vcc, 1.0, v4, 1.0
	v_mul_f32_e32 v20, v12, v10
	v_fma_f32 v22, -v5, v20, v12
	v_fmac_f32_e32 v20, v22, v10
	v_fma_f32 v5, -v5, v20, v12
	v_div_fmas_f32 v5, v5, v10, v20
	v_div_fixup_f32 v10, v5, v4, 1.0
	s_nop 1
	v_mov_b64_e32 v[2:3], v[180:181]
	v_mov_b64_e32 v[4:5], v[182:183]
	v_pk_mul_f32 v[78:79], v[78:79], v[10:11] op_sel_hi:[1,0]
	v_pk_mul_f32 v[80:81], v[80:81], v[10:11] op_sel_hi:[1,0]
	v_pk_mul_f32 v[70:71], v[70:71], v[10:11] op_sel_hi:[1,0]
	v_pk_mul_f32 v[66:67], v[66:67], v[10:11] op_sel_hi:[1,0]
	v_pk_mul_f32 v[62:63], v[62:63], v[10:11] op_sel_hi:[1,0]
	v_pk_mul_f32 v[60:61], v[60:61], v[10:11] op_sel_hi:[1,0]
	v_pk_mul_f32 v[58:59], v[58:59], v[10:11] op_sel_hi:[1,0]
	v_pk_mul_f32 v[52:53], v[52:53], v[10:11] op_sel_hi:[1,0]
	v_pk_mul_f32 v[48:49], v[48:49], v[10:11] op_sel_hi:[1,0]
	v_pk_mul_f32 v[46:47], v[46:47], v[10:11] op_sel_hi:[1,0]
	v_pk_mul_f32 v[40:41], v[40:41], v[10:11] op_sel_hi:[1,0]
	v_pk_mul_f32 v[38:39], v[38:39], v[10:11] op_sel_hi:[1,0]
	v_add_f32_e32 v22, v28, v29
	v_add_f32_e32 v12, v14, v15
	s_add_i32 s8, s8, s26
	s_add_u32 s16, s16, s34
	s_addc_u32 s17, s17, s35
	s_add_u32 s14, s14, s36
	s_addc_u32 s15, s15, s37
	s_cmpk_lt_i32 s8, 0x2000
	s_nop 0
	v_pk_fma_f32 v[2:3], v[2:3], v[78:79], v[86:87]
	v_add_co_u32_e32 v78, vcc, s38, v72
	v_pk_fma_f32 v[4:5], v[4:5], v[80:81], v[88:89]
	s_nop 0
	v_addc_co_u32_e32 v79, vcc, -1, v73, vcc
	global_store_dwordx4 v[78:79], v[2:5], off offset:-3072
	s_nop 1
	v_mov_b64_e32 v[2:3], v[184:185]
	v_mov_b64_e32 v[4:5], v[186:187]
	s_nop 0
	s_nop 1
	v_mov_b64_e32 v[86:87], v[216:217]
	v_mov_b64_e32 v[88:89], v[218:219]
	s_nop 0
	v_pk_fma_f32 v[2:3], v[2:3], v[66:67], v[86:87]
	v_pk_fma_f32 v[4:5], v[4:5], v[70:71], v[88:89]
	global_store_dwordx4 v[78:79], v[2:5], off offset:-2048
	s_nop 1
	v_mov_b64_e32 v[2:3], v[188:189]
	v_mov_b64_e32 v[4:5], v[190:191]
	s_nop 1
	v_mov_b64_e32 v[86:87], v[220:221]
	v_mov_b64_e32 v[88:89], v[222:223]
	v_pk_mul_f32 v[66:67], v[68:69], v[10:11] op_sel_hi:[1,0]
	s_nop 0
	v_pk_fma_f32 v[2:3], v[2:3], v[62:63], v[86:87]
	v_pk_fma_f32 v[4:5], v[4:5], v[66:67], v[88:89]
	global_store_dwordx4 v[78:79], v[2:5], off offset:-1024
	s_nop 1
	v_mov_b64_e32 v[2:3], v[192:193]
	v_mov_b64_e32 v[4:5], v[194:195]
	s_nop 0
	s_nop 1
	v_mov_b64_e32 v[66:67], v[236:237]
	v_mov_b64_e32 v[68:69], v[238:239]
	v_add_co_u32_e32 v62, vcc, s82, v76
	s_nop 0
	v_pk_fma_f32 v[2:3], v[2:3], v[58:59], v[66:67]
	v_pk_fma_f32 v[4:5], v[4:5], v[60:61], v[68:69]
	v_addc_co_u32_e32 v63, vcc, 0, v77, vcc
	global_store_dwordx4 v[72:73], v[2:5], off offset:-4096
	v_add_co_u32_e32 v66, vcc, s82, v74
	s_nop 1
	v_mov_b64_e32 v[2:3], v[196:197]
	v_mov_b64_e32 v[4:5], v[198:199]
	s_nop 0
	v_addc_co_u32_e32 v67, vcc, 0, v75, vcc
	s_nop 1
	v_mov_b64_e32 v[58:59], v[240:241]
	v_mov_b64_e32 v[60:61], v[242:243]
	s_nop 0
	v_pk_fma_f32 v[2:3], v[2:3], v[48:49], v[58:59]
	v_pk_fma_f32 v[4:5], v[4:5], v[52:53], v[60:61]
	global_store_dwordx4 v[72:73], v[2:5], off offset:-3072
	s_nop 1
	v_mov_b64_e32 v[2:3], v[200:201]
	v_mov_b64_e32 v[4:5], v[202:203]
	s_nop 0
	s_nop 1
	v_mov_b64_e32 v[58:59], v[128:129]
	v_mov_b64_e32 v[60:61], v[130:131]
	v_pk_mul_f32 v[48:49], v[64:65], v[10:11] op_sel_hi:[1,0]
	v_pk_mul_f32 v[52:53], v[56:57], v[10:11] op_sel_hi:[1,0]
	s_nop 0
	v_pk_fma_f32 v[4:5], v[4:5], v[48:49], v[60:61]
	v_pk_fma_f32 v[2:3], v[2:3], v[52:53], v[58:59]
	global_store_dwordx4 v[72:73], v[2:5], off offset:-2048
	s_nop 1
	v_mov_b64_e32 v[2:3], v[204:205]
	v_mov_b64_e32 v[4:5], v[206:207]
	s_nop 1
	v_mov_b64_e32 v[56:57], v[132:133]
	v_mov_b64_e32 v[58:59], v[134:135]
	s_nop 0
	v_pk_fma_f32 v[2:3], v[2:3], v[40:41], v[56:57]
	v_pk_fma_f32 v[4:5], v[4:5], v[46:47], v[58:59]
	global_store_dwordx4 v[72:73], v[2:5], off offset:-1024
	s_nop 1
	v_mov_b64_e32 v[2:3], v[208:209]
	v_mov_b64_e32 v[4:5], v[210:211]
	s_nop 0
	s_nop 1
	v_mov_b64_e32 v[46:47], v[140:141]
	v_mov_b64_e32 v[48:49], v[142:143]
	v_pk_mul_f32 v[40:41], v[42:43], v[10:11] op_sel_hi:[1,0]
	v_and_b32_e32 v43, 0xffff0000, v31
	v_and_b32_e32 v42, 0xffff0000, v30
	v_add_f32_e32 v10, v16, v17
	s_nop 0
	v_pk_fma_f32 v[2:3], v[38:39], v[2:3], v[46:47]
	v_pk_fma_f32 v[4:5], v[40:41], v[4:5], v[48:49]
	v_lshlrev_b32_e32 v38, 16, v34
	v_lshlrev_b32_e32 v39, 16, v36
	v_and_b32_e32 v47, 0xffff0000, v36
	v_and_b32_e32 v46, 0xffff0000, v34
	v_and_b32_e32 v49, 0xffff0000, v37
	v_and_b32_e32 v48, 0xffff0000, v35
	global_store_dwordx4 v[72:73], v[2:5], off
	v_and_b32_e32 v41, 0xffff0000, v33
	v_and_b32_e32 v40, 0xffff0000, v32
	v_pk_add_f32 v[2:3], v[38:39], v[46:47]
	v_pk_add_f32 v[4:5], v[44:45], v[48:49]
	s_nop 0
	v_pk_add_f32 v[2:3], v[2:3], v[4:5]
	v_lshlrev_b32_e32 v5, 16, v33
	v_add_f32_e32 v2, 0, v2
	v_lshlrev_b32_e32 v4, 16, v32
	v_add_f32_e32 v20, v2, v3
	v_pk_add_f32 v[2:3], v[4:5], v[40:41]
	v_pk_add_f32 v[32:33], v[24:25], v[22:23]
	v_pk_add_f32 v[2:3], v[2:3], v[2:3] op_sel:[0,1] op_sel_hi:[1,0]
	s_nop 0
	v_mov_b32_e32 v3, v19
	v_pk_add_f32 v[2:3], v[20:21], v[2:3]
	s_nop 0
	v_pk_add_f32 v[32:33], v[2:3], v[32:33]
	v_lshlrev_b32_e32 v3, 16, v31
	v_lshlrev_b32_e32 v2, 16, v30
	v_pk_add_f32 v[30:31], v[2:3], v[42:43]
	v_pk_add_f32 v[32:33], v[32:33], v[32:33] op_sel:[0,1] op_sel_hi:[1,0]
	v_pk_add_f32 v[30:31], v[30:31], v[30:31] op_sel:[0,1] op_sel_hi:[1,0]
	v_mov_b32_e32 v33, v8
	v_mov_b32_e32 v31, v9
	v_pk_add_f32 v[30:31], v[32:33], v[30:31]
	v_pk_add_f32 v[32:33], v[12:13], v[10:11]
	s_nop 0
	v_pk_add_f32 v[30:31], v[30:31], v[32:33]
	s_nop 0
	v_add_f32_e32 v10, v30, v31
	ds_bpermute_b32 v12, v7, v10
	s_waitcnt lgkmcnt(0)
	v_add_f32_e32 v10, v10, v12
	ds_bpermute_b32 v12, v18, v10
	s_waitcnt lgkmcnt(0)
	v_add_f32_e32 v10, v10, v12
	ds_bpermute_b32 v12, v50, v10
	s_waitcnt lgkmcnt(0)
	v_add_f32_e32 v10, v10, v12
	ds_bpermute_b32 v12, v54, v10
	s_waitcnt lgkmcnt(0)
	v_add_f32_e32 v10, v10, v12
	ds_bpermute_b32 v12, v82, v10
	s_waitcnt lgkmcnt(0)
	v_add_f32_e32 v10, v10, v12
	ds_bpermute_b32 v12, v84, v10
	s_waitcnt lgkmcnt(0)
	v_add_f32_e32 v12, v10, v12
	v_fmac_f32_e32 v48, 0xba000000, v12
	v_fmac_f32_e32 v46, 0xba000000, v12
	v_fmac_f32_e32 v49, 0xba000000, v12
	v_fmac_f32_e32 v47, 0xba000000, v12
	v_fmac_f32_e32 v44, 0xba000000, v12
	v_fmac_f32_e32 v38, 0xba000000, v12
	v_fmac_f32_e32 v45, 0xba000000, v12
	v_fmac_f32_e32 v39, 0xba000000, v12
	v_mov_b32_e32 v31, v47
	v_mov_b32_e32 v35, v46
	v_pk_mul_f32 v[32:33], v[46:47], v[46:47]
	v_pk_mul_f32 v[46:47], v[48:49], v[48:49]
	v_mov_b32_e32 v30, v39
	v_mov_b32_e32 v34, v38
	v_pk_fma_f32 v[38:39], v[38:39], v[38:39], v[32:33]
	v_mov_b32_e32 v32, v45
	v_mov_b32_e32 v36, v44
	v_pk_fma_f32 v[44:45], v[44:45], v[44:45], v[46:47]
	v_fmac_f32_e32 v40, 0xba000000, v12
	v_pk_add_f32 v[38:39], v[38:39], v[44:45]
	v_fmac_f32_e32 v41, 0xba000000, v12
	v_fmac_f32_e32 v5, 0xba000000, v12
	v_pk_add_f32 v[44:45], v[38:39], v[38:39] op_sel_hi:[0,1]
	v_fmac_f32_e32 v4, 0xba000000, v12
	v_mov_b32_e32 v38, v5
	v_mov_b32_e32 v39, v41
	v_mov_b32_e32 v5, v40
	v_pk_mul_f32 v[46:47], v[38:39], v[38:39]
	v_pk_mul_f32 v[40:41], v[4:5], v[4:5]
	v_fmac_f32_e32 v26, 0xba000000, v12
	v_mov_b32_e32 v33, v49
	v_mov_b32_e32 v37, v48
	v_pk_mov_b32 v[48:49], v[40:41], v[46:47] op_sel:[1,0]
	v_mov_b32_e32 v41, v47
	v_fmac_f32_e32 v27, 0xba000000, v12
	v_fmac_f32_e32 v28, 0xba000000, v12
	v_mul_f32_e32 v10, v26, v26
	v_pk_add_f32 v[40:41], v[48:49], v[40:41]
	v_fmac_f32_e32 v29, 0xba000000, v12
	v_pk_fma_f32 v[46:47], v[26:27], v[26:27], v[10:11] op_sel_hi:[1,1,0]
	v_mul_f32_e32 v10, v28, v28
	v_pk_add_f32 v[40:41], v[40:41], v[40:41] op_sel_hi:[0,1]
	v_pk_fma_f32 v[48:49], v[28:29], v[28:29], v[10:11] op_sel_hi:[1,1,0]
	v_fmac_f32_e32 v23, 0xba000000, v12
	v_fmac_f32_e32 v25, 0xba000000, v12
	v_fmac_f32_e32 v19, 0xba000000, v12
	v_fmac_f32_e32 v21, 0xba000000, v12
	v_mul_f32_e32 v46, v21, v21
	v_mul_f32_e32 v48, v19, v19
	v_mul_f32_e32 v40, v25, v25
	v_mul_f32_e32 v44, v23, v23
	v_pk_add_f32 v[46:47], v[46:47], v[48:49]
	v_pk_add_f32 v[40:41], v[40:41], v[44:45]
	v_fmac_f32_e32 v42, 0xba000000, v12
	v_pk_add_f32 v[40:41], v[46:47], v[40:41]
	v_fmac_f32_e32 v43, 0xba000000, v12
	v_fmac_f32_e32 v3, 0xba000000, v12
	v_pk_add_f32 v[44:45], v[40:41], v[40:41] op_sel_hi:[0,1]
	v_fmac_f32_e32 v2, 0xba000000, v12
	v_mov_b32_e32 v40, v3
	v_mov_b32_e32 v41, v43
	v_mov_b32_e32 v3, v42
	v_pk_mul_f32 v[46:47], v[40:41], v[40:41]
	v_pk_mul_f32 v[42:43], v[2:3], v[2:3]
	v_fmac_f32_e32 v14, 0xba000000, v12
	v_pk_mov_b32 v[48:49], v[42:43], v[46:47] op_sel:[1,0]
	v_mov_b32_e32 v43, v47
	v_fmac_f32_e32 v15, 0xba000000, v12
	v_fmac_f32_e32 v16, 0xba000000, v12
	v_mul_f32_e32 v10, v14, v14
	v_pk_add_f32 v[42:43], v[48:49], v[42:43]
	v_fmac_f32_e32 v17, 0xba000000, v12
	v_pk_fma_f32 v[46:47], v[14:15], v[14:15], v[10:11] op_sel_hi:[1,1,0]
	v_mul_f32_e32 v10, v16, v16
	v_pk_add_f32 v[42:43], v[42:43], v[42:43] op_sel_hi:[0,1]
	v_pk_fma_f32 v[48:49], v[16:17], v[16:17], v[10:11] op_sel_hi:[1,1,0]
	v_fmac_f32_e32 v11, 0xba000000, v12
	v_fmac_f32_e32 v13, 0xba000000, v12
	v_fmac_f32_e32 v9, 0xba000000, v12
	v_fmac_f32_e32 v8, 0xba000000, v12
	v_mul_f32_e32 v46, v8, v8
	v_mul_f32_e32 v48, v9, v9
	v_mul_f32_e32 v42, v13, v13
	v_mul_f32_e32 v44, v11, v11
	v_pk_add_f32 v[46:47], v[46:47], v[48:49]
	v_pk_add_f32 v[42:43], v[42:43], v[44:45]
	s_nop 0
	v_pk_add_f32 v[42:43], v[46:47], v[42:43]
	s_nop 0
	v_add_f32_e32 v10, v42, v43
	ds_bpermute_b32 v7, v7, v10
	v_lshlrev_b32_e32 v42, 2, v1
	v_ashrrev_i32_e32 v43, 31, v42
	s_waitcnt lgkmcnt(0)
	v_add_f32_e32 v7, v10, v7
	ds_bpermute_b32 v10, v18, v7
	s_waitcnt lgkmcnt(0)
	v_add_f32_e32 v7, v7, v10
	ds_bpermute_b32 v10, v50, v7
	s_waitcnt lgkmcnt(0)
	v_add_f32_e32 v7, v7, v10
	ds_bpermute_b32 v10, v54, v7
	v_lshlrev_b64 v[54:55], 2, v[42:43]
	v_lshl_add_u64 v[44:45], s[20:21], 0, v[54:55]
	v_lshl_add_u64 v[42:43], s[18:19], 0, v[54:55]
	s_nop 1
	v_mov_b64_e32 v[46:47], v[180:181]
	v_mov_b64_e32 v[48:49], v[182:183]
	s_nop 1
	v_mov_b64_e32 v[50:51], v[212:213]
	v_mov_b64_e32 v[52:53], v[214:215]
	s_waitcnt lgkmcnt(0)
	v_add_f32_e32 v7, v7, v10
	ds_bpermute_b32 v10, v82, v7
	s_waitcnt lgkmcnt(0)
	v_add_f32_e32 v7, v7, v10
	ds_bpermute_b32 v10, v84, v7
	s_waitcnt lgkmcnt(0)
	v_add_f32_e32 v7, v7, v10
	v_fmamk_f32 v7, v7, 0x3a000000, v250
	v_cmp_gt_f32_e32 vcc, s96, v7
	v_mul_f32_e32 v10, 0x4f800000, v7
	s_nop 0
	v_cndmask_b32_e32 v7, v7, v10, vcc
	v_sqrt_f32_e32 v10, v7
	s_nop 0
	v_add_u32_e32 v12, -1, v10
	v_fma_f32 v18, -v12, v10, v7
	v_cmp_ge_f32_e64 s[10:11], 0, v18
	v_add_u32_e32 v18, 1, v10
	s_nop 0
	v_cndmask_b32_e64 v12, v10, v12, s[10:11]
	v_fma_f32 v10, -v18, v10, v7
	v_cmp_lt_f32_e64 s[10:11], 0, v10
	s_nop 1
	v_cndmask_b32_e64 v10, v12, v18, s[10:11]
	v_mul_f32_e32 v12, 0x37800000, v10
	v_cndmask_b32_e32 v10, v10, v12, vcc
	v_cmp_class_f32_e32 vcc, v7, v251
	s_nop 1
	v_cndmask_b32_e32 v7, v10, v7, vcc
	v_div_scale_f32 v10, s[10:11], v7, v7, 1.0
	v_rcp_f32_e32 v12, v10
	s_nop 0
	v_fma_f32 v18, -v10, v12, 1.0
	v_fmac_f32_e32 v12, v18, v12
	v_div_scale_f32 v18, vcc, 1.0, v7, 1.0
	v_mul_f32_e32 v20, v18, v12
	v_fma_f32 v22, -v10, v20, v18
	v_fmac_f32_e32 v20, v22, v12
	v_fma_f32 v10, -v10, v20, v18
	v_div_fmas_f32 v10, v10, v12, v20
	v_div_fixup_f32 v12, v10, v7, 1.0
	v_pk_mul_f32 v[36:37], v[36:37], v[12:13] op_sel_hi:[1,0]
	v_pk_mul_f32 v[34:35], v[34:35], v[12:13] op_sel_hi:[1,0]
	v_pk_mul_f32 v[32:33], v[32:33], v[12:13] op_sel_hi:[1,0]
	v_pk_mul_f32 v[30:31], v[30:31], v[12:13] op_sel_hi:[1,0]
	v_pk_mul_f32 v[38:39], v[38:39], v[12:13] op_sel_hi:[1,0]
	v_pk_mul_f32 v[4:5], v[4:5], v[12:13] op_sel_hi:[1,0]
	v_pk_mul_f32 v[26:27], v[26:27], v[12:13] op_sel_hi:[1,0]
	v_mov_b32_e32 v18, v21
	v_mov_b32_e32 v22, v25
	v_pk_mul_f32 v[18:19], v[18:19], v[12:13] op_sel_hi:[1,0]
	v_pk_mul_f32 v[2:3], v[2:3], v[12:13] op_sel_hi:[1,0]
	v_pk_mul_f32 v[16:17], v[16:17], v[12:13] op_sel_hi:[1,0]
	v_pk_mul_f32 v[14:15], v[14:15], v[12:13] op_sel_hi:[1,0]
	v_mov_b32_e32 v10, v13
	v_pk_mul_f32 v[10:11], v[10:11], v[12:13] op_sel_hi:[1,0]
	v_pk_mul_f32 v[8:9], v[8:9], v[12:13] op_sel_hi:[1,0]
	s_nop 0
	v_pk_fma_f32 v[34:35], v[46:47], v[34:35], v[50:51]
	v_pk_fma_f32 v[36:37], v[48:49], v[36:37], v[52:53]
	v_lshl_add_u64 v[50:51], s[22:23], 0, v[54:55]
	global_store_dwordx4 v[50:51], v[34:37], off
	s_nop 1
	v_mov_b64_e32 v[34:35], v[184:185]
	v_mov_b64_e32 v[36:37], v[186:187]
	s_nop 0
	s_nop 1
	v_mov_b64_e32 v[46:47], v[216:217]
	v_mov_b64_e32 v[48:49], v[218:219]
	s_nop 0
	v_pk_fma_f32 v[30:31], v[34:35], v[30:31], v[46:47]
	v_pk_fma_f32 v[32:33], v[36:37], v[32:33], v[48:49]
	global_store_dwordx4 v[50:51], v[30:33], off offset:1024
	s_nop 1
	v_mov_b64_e32 v[30:31], v[188:189]
	v_mov_b64_e32 v[32:33], v[190:191]
	s_nop 1
	v_mov_b64_e32 v[34:35], v[220:221]
	v_mov_b64_e32 v[36:37], v[222:223]
	s_nop 0
	v_pk_fma_f32 v[30:31], v[30:31], v[4:5], v[34:35]
	v_pk_fma_f32 v[32:33], v[32:33], v[38:39], v[36:37]
	global_store_dwordx4 v[50:51], v[30:33], off offset:2048
	s_nop 1
	v_mov_b64_e32 v[30:31], v[192:193]
	v_mov_b64_e32 v[32:33], v[194:195]
	s_nop 0
	s_nop 1
	v_mov_b64_e32 v[34:35], v[236:237]
	v_mov_b64_e32 v[36:37], v[238:239]
	v_pk_mul_f32 v[4:5], v[28:29], v[12:13] op_sel_hi:[1,0]
	s_nop 0
	v_pk_fma_f32 v[26:27], v[30:31], v[26:27], v[34:35]
	v_add_co_u32_e32 v34, vcc, s82, v44
	v_pk_fma_f32 v[28:29], v[32:33], v[4:5], v[36:37]
	s_nop 0
	v_addc_co_u32_e32 v35, vcc, 0, v45, vcc
	global_store_dwordx4 v[50:51], v[26:29], off offset:3072
	v_add_co_u32_e32 v36, vcc, s82, v42
	s_nop 1
	v_mov_b64_e32 v[26:27], v[196:197]
	v_mov_b64_e32 v[28:29], v[198:199]
	s_nop 0
	v_addc_co_u32_e32 v37, vcc, 0, v43, vcc
	s_nop 1
	v_mov_b64_e32 v[30:31], v[240:241]
	v_mov_b64_e32 v[32:33], v[242:243]
	v_pk_mul_f32 v[4:5], v[22:23], v[12:13] op_sel_hi:[1,0]
	s_nop 0
	v_pk_fma_f32 v[18:19], v[26:27], v[18:19], v[30:31]
	v_add_co_u32_e32 v26, vcc, s82, v50
	v_pk_fma_f32 v[20:21], v[28:29], v[4:5], v[32:33]
	s_nop 0
	v_addc_co_u32_e32 v27, vcc, 0, v51, vcc
	global_store_dwordx4 v[26:27], v[18:21], off
	s_nop 1
	v_mov_b64_e32 v[18:19], v[200:201]
	v_mov_b64_e32 v[20:21], v[202:203]
	s_nop 0
	s_nop 1
	v_mov_b64_e32 v[22:23], v[128:129]
	v_mov_b64_e32 v[24:25], v[130:131]
	v_pk_mul_f32 v[4:5], v[40:41], v[12:13] op_sel_hi:[1,0]
	s_nop 0
	v_pk_fma_f32 v[2:3], v[18:19], v[2:3], v[22:23]
	v_pk_fma_f32 v[4:5], v[20:21], v[4:5], v[24:25]
	global_store_dwordx4 v[26:27], v[2:5], off offset:1024
	s_nop 1
	v_mov_b64_e32 v[2:3], v[204:205]
	v_mov_b64_e32 v[4:5], v[206:207]
	s_nop 1
	v_mov_b64_e32 v[18:19], v[132:133]
	v_mov_b64_e32 v[20:21], v[134:135]
	s_nop 0
	v_pk_fma_f32 v[2:3], v[2:3], v[14:15], v[18:19]
	v_pk_fma_f32 v[4:5], v[4:5], v[16:17], v[20:21]
	global_store_dwordx4 v[26:27], v[2:5], off offset:2048
	s_nop 1
	v_mov_b64_e32 v[2:3], v[208:209]
	v_mov_b64_e32 v[4:5], v[210:211]
	s_nop 0
	s_nop 1
	v_mov_b64_e32 v[14:15], v[140:141]
	v_mov_b64_e32 v[16:17], v[142:143]
	s_nop 0
	v_pk_fma_f32 v[2:3], v[8:9], v[2:3], v[14:15]
	v_pk_fma_f32 v[4:5], v[10:11], v[4:5], v[16:17]
	global_store_dwordx4 v[26:27], v[2:5], off offset:3072
	s_cbranch_scc1 .LBB0_1705
